# attB: V operand fetched with 16 dword gathers per key block instead of 32 ushort gathers (P0 stores the vb weight rows so that a dword holds dv m and dv 32+m; accumulators and output layout unchanged)
# speedup vs baseline: 1.0012x; 1.0012x over previous
; #define LAS __attribute__((address_space(3)))
; __device__ __forceinline__ unsigned cvtpk(float lo, float hi) { return pg8::cvt_pk_bf16(lo, hi); }
; __device__ __forceinline__ void transpose_item(const float* W, int K, int N, int c0, int ncols, bf16_t* WT, int row_off, float scale, LAS float* scr, int item, int lane) {
;     const int nblk = ncols / 32, kb = item / nblk, nb = item % nblk, k0 = 64 * kb, n0 = 32 * nb;
; #pragma unroll 8
;     for (int i = 0; i < 32; ++i) { const int kk = 2 * i + (lane >> 5); scr[kk * 33 + (lane & 31)] = W[(size_t)(k0 + kk) * N + c0 + n0 + (lane & 31)] * scale; }
;     asm volatile("s_waitcnt lgkmcnt(0)" ::: "memory");
;     const int c = lane & 7;
; #pragma unroll
;     for (int j = 0; j < 4; ++j) { const int n = (lane >> 3) + 8 * j; const LAS float* s = scr + (8 * c) * 33 + n;
;         u32x4 o; o.x = cvtpk(s[0 * 33], s[1 * 33]); o.y = cvtpk(s[2 * 33], s[3 * 33]); o.z = cvtpk(s[4 * 33], s[5 * 33]); o.w = cvtpk(s[6 * 33], s[7 * 33]);
;         *(u32x4*)(WT + (size_t)(row_off + n0 + n) * K + k0 + 8 * c) = o; }
;     asm volatile("s_waitcnt lgkmcnt(0)" ::: "memory");
; }
.LBB0_59:
	s_lshl_b32 s37, s15, 1
	s_lshl_b32 s40, s31, 1
	v_or_b32_e32 v29, s37, v3
	v_or_b32_e32 v30, s40, v4
	s_add_i32 s41, s37, 4
	s_add_i32 s42, s40, 4
	s_add_i32 s43, s37, 8
	s_add_i32 s44, s40, 8
	s_add_i32 s45, s37, 12
	s_add_i32 s46, s40, 12
	s_add_i32 s47, s37, 16
	s_add_i32 s48, s40, 16
	s_add_i32 s49, s37, 20
	s_add_i32 s50, s40, 20
	s_add_i32 s51, s37, 24
	s_add_i32 s52, s40, 24
	s_add_i32 s53, s37, 28
	s_add_i32 s54, s40, 28
	v_mad_i64_i32 v[30:31], s[38:39], v30, s34, v[22:23]
	v_mad_i64_i32 v[32:33], s[38:39], v29, s34, v[22:23]
	v_or_b32_e32 v29, s41, v3
	v_or_b32_e32 v34, s42, v4
	v_or_b32_e32 v40, s43, v3
	v_or_b32_e32 v38, s44, v4
	v_or_b32_e32 v44, s45, v3
	v_or_b32_e32 v42, s46, v4
	v_or_b32_e32 v48, s47, v3
	v_or_b32_e32 v46, s48, v4
	v_or_b32_e32 v52, s49, v3
	v_or_b32_e32 v50, s50, v4
	v_or_b32_e32 v56, s51, v3
	v_or_b32_e32 v54, s52, v4
	v_or_b32_e32 v60, s53, v3
	v_or_b32_e32 v58, s54, v4
	v_mad_i64_i32 v[34:35], s[38:39], v34, s34, v[22:23]
	v_mad_i64_i32 v[36:37], s[38:39], v29, s34, v[22:23]
	v_mad_i64_i32 v[38:39], s[38:39], v38, s34, v[22:23]
	v_mad_i64_i32 v[40:41], s[38:39], v40, s34, v[22:23]
	v_mad_i64_i32 v[42:43], s[38:39], v42, s34, v[22:23]
	v_mad_i64_i32 v[44:45], s[38:39], v44, s34, v[22:23]
	v_mad_i64_i32 v[46:47], s[38:39], v46, s34, v[22:23]
	v_mad_i64_i32 v[48:49], s[38:39], v48, s34, v[22:23]
	v_mad_i64_i32 v[50:51], s[38:39], v50, s34, v[22:23]
	v_mad_i64_i32 v[52:53], s[38:39], v52, s34, v[22:23]
	v_mad_i64_i32 v[54:55], s[38:39], v54, s34, v[22:23]
	v_mad_i64_i32 v[56:57], s[38:39], v56, s34, v[22:23]
	v_mad_i64_i32 v[58:59], s[38:39], v58, s34, v[22:23]
	v_mad_i64_i32 v[60:61], s[38:39], v60, s34, v[22:23]
	global_load_dword v29, v[30:31], off
	global_load_dword v62, v[32:33], off
	global_load_dword v63, v[34:35], off
	global_load_dword v64, v[36:37], off
	global_load_dword v65, v[38:39], off
	global_load_dword v66, v[40:41], off
	global_load_dword v67, v[42:43], off
	global_load_dword v68, v[44:45], off
	global_load_dword v69, v[46:47], off
	global_load_dword v70, v[48:49], off
	global_load_dword v71, v[50:51], off
	global_load_dword v72, v[52:53], off
	global_load_dword v73, v[54:55], off
	global_load_dword v74, v[56:57], off
	global_load_dword v75, v[58:59], off
	global_load_dword v76, v[60:61], off
	v_or_b32_e32 v32, s37, v1
	v_or_b32_e32 v30, s40, v0
	s_add_i32 s31, s31, 16
	s_add_i32 s15, s15, 16
	s_add_i32 s36, s36, -16
	v_mad_u64_u32 v[30:31], s[38:39], v30, s33, v[2:3]
	v_mad_u64_u32 v[32:33], s[38:39], v32, s33, v[2:3]
	v_or_b32_e32 v31, s41, v1
	v_or_b32_e32 v33, s42, v0
	v_or_b32_e32 v40, s43, v1
	v_or_b32_e32 v38, s44, v0
	v_or_b32_e32 v44, s45, v1
	v_or_b32_e32 v42, s46, v0
	v_or_b32_e32 v48, s47, v1
	v_or_b32_e32 v46, s48, v0
	v_or_b32_e32 v52, s49, v1
	v_or_b32_e32 v50, s50, v0
	v_or_b32_e32 v56, s51, v1
	v_or_b32_e32 v54, s52, v0
	v_or_b32_e32 v60, s53, v1
	v_or_b32_e32 v58, s54, v0
	s_cmp_lg_u32 s36, 0
	v_mad_u64_u32 v[34:35], s[38:39], v33, s33, v[2:3]
	v_mad_u64_u32 v[36:37], s[38:39], v31, s33, v[2:3]
	v_mad_u64_u32 v[38:39], s[38:39], v38, s33, v[2:3]
	v_mad_u64_u32 v[40:41], s[38:39], v40, s33, v[2:3]
	v_mad_u64_u32 v[42:43], s[38:39], v42, s33, v[2:3]
	v_mad_u64_u32 v[44:45], s[38:39], v44, s33, v[2:3]
	v_mad_u64_u32 v[46:47], s[38:39], v46, s33, v[2:3]
	v_mad_u64_u32 v[48:49], s[38:39], v48, s33, v[2:3]
	v_mad_u64_u32 v[50:51], s[38:39], v50, s33, v[2:3]
	v_mad_u64_u32 v[52:53], s[38:39], v52, s33, v[2:3]
	v_mad_u64_u32 v[54:55], s[38:39], v54, s33, v[2:3]
	v_mad_u64_u32 v[56:57], s[38:39], v56, s33, v[2:3]
	v_mad_u64_u32 v[58:59], s[38:39], v58, s33, v[2:3]
	v_mad_u64_u32 v[60:61], s[38:39], v60, s33, v[2:3]
	s_waitcnt vmcnt(15)
	ds_write_b32 v30, v29
	s_waitcnt vmcnt(14)
	ds_write_b32 v32, v62
	s_waitcnt vmcnt(13)
	ds_write_b32 v34, v63
	s_waitcnt vmcnt(12)
	ds_write_b32 v36, v64
	s_waitcnt vmcnt(11)
	ds_write_b32 v38, v65
	s_waitcnt vmcnt(10)
	ds_write_b32 v40, v66
	s_waitcnt vmcnt(9)
	ds_write_b32 v42, v67
	s_waitcnt vmcnt(8)
	ds_write_b32 v44, v68
	s_waitcnt vmcnt(7)
	ds_write_b32 v46, v69
	s_waitcnt vmcnt(6)
	ds_write_b32 v48, v70
	s_waitcnt vmcnt(5)
	ds_write_b32 v50, v71
	s_waitcnt vmcnt(4)
	ds_write_b32 v52, v72
	s_waitcnt vmcnt(3)
	ds_write_b32 v54, v73
	s_waitcnt vmcnt(2)
	ds_write_b32 v56, v74
	s_waitcnt vmcnt(1)
	ds_write_b32 v58, v75
	s_waitcnt vmcnt(0)
	ds_write_b32 v60, v76
	s_cbranch_scc1 .LBB0_59
	s_waitcnt lgkmcnt(0)
	ds_read2_b32 v[22:23], v25 offset0:33 offset1:41
	ds_read2_b32 v[34:35], v25 offset1:8
	ds_read2_b32 v[36:37], v25 offset0:66 offset1:74
	ds_read2_b32 v[38:39], v25 offset0:99 offset1:107
	ds_read2_b32 v[40:41], v25 offset0:132 offset1:140
	ds_read2_b32 v[42:43], v25 offset0:165 offset1:173
	ds_read2_b32 v[44:45], v25 offset0:198 offset1:206
	ds_read2_b32 v[46:47], v25 offset0:231 offset1:239
	s_bfe_u32 s37, s30, 0x10005
	s_and_b32 s30, s30, 0xffffffc0
	s_or_b32 s30, s30, s37
	s_addk_i32 s30, 0x1400
	s_ashr_i32 s15, s14, 31
	v_lshl_or_b32 v4, v24, 1, s30
	v_lshl_add_u64 v[48:49], s[14:15], 1, v[6:7]
	v_lshlrev_b64 v[50:51], 11, v[4:5]
	s_waitcnt lgkmcnt(6)
	v_cvt_pk_bf16_f32 v30, v34, v22
	s_waitcnt lgkmcnt(4)
	v_cvt_pk_bf16_f32 v31, v36, v38
	s_waitcnt lgkmcnt(2)
	v_cvt_pk_bf16_f32 v32, v40, v42
	s_waitcnt lgkmcnt(0)
	v_cvt_pk_bf16_f32 v33, v44, v46
	v_lshl_add_u64 v[50:51], v[48:49], 0, v[50:51]
	global_store_dwordx4 v[50:51], v[30:33], off
	v_lshl_or_b32 v4, v26, 1, s30
	s_nop 0
	v_cvt_pk_bf16_f32 v30, v35, v23
	v_cvt_pk_bf16_f32 v31, v37, v39
	v_cvt_pk_bf16_f32 v32, v41, v43
	v_cvt_pk_bf16_f32 v33, v45, v47
	ds_read2_b32 v[34:35], v25 offset0:49 offset1:57
	ds_read2_b32 v[36:37], v25 offset0:16 offset1:24
	ds_read2_b32 v[38:39], v25 offset0:82 offset1:90
	ds_read2_b32 v[40:41], v25 offset0:115 offset1:123
	ds_read2_b32 v[42:43], v25 offset0:148 offset1:156
	ds_read2_b32 v[44:45], v25 offset0:181 offset1:189
	ds_read2_b32 v[46:47], v25 offset0:214 offset1:222
	ds_read2_b32 v[50:51], v25 offset0:247 offset1:255
	v_lshlrev_b64 v[22:23], 11, v[4:5]
	v_lshl_add_u64 v[22:23], v[48:49], 0, v[22:23]
	v_lshl_or_b32 v4, v27, 1, s30
	global_store_dwordx4 v[22:23], v[30:33], off
	v_lshlrev_b64 v[22:23], 11, v[4:5]
	v_lshl_add_u64 v[22:23], v[48:49], 0, v[22:23]
	s_waitcnt lgkmcnt(6)
	v_cvt_pk_bf16_f32 v30, v36, v34
	s_waitcnt lgkmcnt(4)
	v_cvt_pk_bf16_f32 v31, v38, v40
	s_waitcnt lgkmcnt(2)
	v_cvt_pk_bf16_f32 v32, v42, v44
	s_waitcnt lgkmcnt(0)
	v_cvt_pk_bf16_f32 v33, v46, v50
	v_lshl_or_b32 v4, v28, 1, s30
	global_store_dwordx4 v[22:23], v[30:33], off
	v_lshlrev_b64 v[22:23], 11, v[4:5]
	v_lshl_add_u64 v[22:23], v[48:49], 0, v[22:23]
	v_cvt_pk_bf16_f32 v30, v37, v35
	v_cvt_pk_bf16_f32 v31, v39, v41
	v_cvt_pk_bf16_f32 v32, v43, v45
	v_cvt_pk_bf16_f32 v33, v47, v51
	global_store_dwordx4 v[22:23], v[30:33], off
	s_waitcnt lgkmcnt(0)

; #define LAS __attribute__((address_space(3)))
; __device__ __forceinline__ int crow(int r, int hi) { return (r & 3) + 8 * (r >> 2) + 4 * hi; }
; __device__ __forceinline__ float ex2(float v) { return __builtin_amdgcn_exp2f(v); }
; __device__ __forceinline__ void unit(LAS unsigned char* lds, bf16_t* P1, int b, int h, int chunk) {
;     LAS float* Os = (LAS float*)lds; LAS float* Ms = (LAS float*)(lds + 131072); LAS float* Ls = Ms + 512;
;     const int tid = threadIdx.x, lane = tid & 63, wid = __builtin_amdgcn_readfirstlane(tid >> 6), r32 = lane & 31, hi = lane >> 5;
;     const int t0 = chunk * 512; const size_t rowbase = (size_t)b * SEQ;
;     const float sl2 = ex2(-(float)(h + 1)) * LOG2E;
;     for (int g = 0; g < 3; ++g) {
;         const int sh = 2 * g; const float sd = sl2 * (float)(1 << sh);
;         f32x16 cb;
; #pragma unroll
;         for (int r = 0; r < 16; ++r) cb[r] = sd * (float)crow(r, hi);
;         for (int wt = wid; wt < 16; wt += 8) {
;             const int cls = wt >> (4 - sh), sub = wt & ((16 >> sh) - 1);
;             const int i0 = (t0 >> sh) + 32 * sub, iq = i0 + r32, tq = (iq << sh) + cls;
; __global__ void __launch_bounds__(NTHR, 2) fwd_kernel(Ptrs P) {
;     ...
;         float lam;
;         { const float a = P.lq1[lane] * P.lk1[lane], b2 = P.lq2[lane] * P.lk2[lane]; lam = expf(wave_sum(a)) - expf(wave_sum(b2)) + 0.2f; }
;         __syncthreads();
; #pragma unroll 1
;         for (int u = vcu; u < 256; u += G) attB::unit(lds, P1, u >> 6, (u >> 3) & 7, u & 7);
.LBB0_311:
	s_cmp_lt_i32 s88, 3
	s_cselect_b64 s[14:15], -1, 0
	s_and_b64 s[0:1], s[14:15], s[0:1]
	s_andn2_b64 vcc, exec, s[0:1]
	s_cbranch_vccnz .LBB0_424
	v_lshlrev_b32_e32 v0, 2, v200
	s_waitcnt lgkmcnt(0)
	global_load_dword v1, v0, s[18:19]
	global_load_dword v2, v0, s[20:21]
	global_load_dword v3, v0, s[22:23]
	global_load_dword v4, v0, s[24:25]
	v_mbcnt_lo_u32_b32 v0, -1, 0
	v_mbcnt_hi_u32_b32 v0, -1, v0
	v_and_b32_e32 v5, 64, v0
	v_xor_b32_e32 v6, 1, v0
	v_add_u32_e32 v5, 64, v5
	v_cmp_lt_i32_e32 vcc, v6, v5
	v_xor_b32_e32 v7, 2, v0
	v_xor_b32_e32 v8, 4, v0
	v_cndmask_b32_e32 v6, v0, v6, vcc
	v_lshlrev_b32_e32 v6, 2, v6
	v_cmp_lt_i32_e32 vcc, v7, v5
	v_xor_b32_e32 v9, 8, v0
	v_xor_b32_e32 v10, 16, v0
	v_cndmask_b32_e32 v7, v0, v7, vcc
	v_lshlrev_b32_e32 v7, 2, v7
	v_cmp_lt_i32_e32 vcc, v8, v5
	v_xor_b32_e32 v11, 32, v0
	s_mov_b32 s0, 0x3fb8aa3b
	s_mov_b32 s1, 0xc2ce8ed0
	s_mov_b32 s2, 0x42b17218
	s_mov_b32 s11, 0
	s_cmpk_gt_i32 s10, 0xff
	v_and_b32_e32 v114, 31, v176
	s_waitcnt vmcnt(0)
	s_barrier
	v_mul_f32_e32 v12, v1, v2
	ds_bpermute_b32 v12, v6, v12
	v_mul_f32_e32 v13, v3, v4
	ds_bpermute_b32 v6, v6, v13
	s_waitcnt lgkmcnt(1)
	v_fmac_f32_e32 v12, v1, v2
	ds_bpermute_b32 v1, v7, v12
	s_waitcnt lgkmcnt(1)
	v_fmac_f32_e32 v6, v3, v4
	ds_bpermute_b32 v2, v7, v6
	v_cndmask_b32_e32 v3, v0, v8, vcc
	v_lshlrev_b32_e32 v3, 2, v3
	s_waitcnt lgkmcnt(1)
	v_add_f32_e32 v1, v12, v1
	ds_bpermute_b32 v4, v3, v1
	s_waitcnt lgkmcnt(1)
	v_add_f32_e32 v2, v6, v2
	ds_bpermute_b32 v3, v3, v2
	v_cmp_lt_i32_e32 vcc, v9, v5
	s_waitcnt lgkmcnt(1)
	v_add_f32_e32 v1, v1, v4
	v_cndmask_b32_e32 v6, v0, v9, vcc
	v_lshlrev_b32_e32 v6, 2, v6
	s_waitcnt lgkmcnt(0)
	v_add_f32_e32 v2, v2, v3
	ds_bpermute_b32 v3, v6, v1
	ds_bpermute_b32 v4, v6, v2
	v_cmp_lt_i32_e32 vcc, v10, v5
	s_waitcnt lgkmcnt(1)
	v_add_f32_e32 v1, v1, v3
	v_cndmask_b32_e32 v6, v0, v10, vcc
	v_lshlrev_b32_e32 v6, 2, v6
	s_waitcnt lgkmcnt(0)
	v_add_f32_e32 v2, v2, v4
	ds_bpermute_b32 v3, v6, v1
	ds_bpermute_b32 v4, v6, v2
	v_cmp_lt_i32_e32 vcc, v11, v5
	s_nop 1
	v_cndmask_b32_e32 v0, v0, v11, vcc
	v_lshlrev_b32_e32 v115, 2, v0
	s_waitcnt lgkmcnt(1)
	v_add_f32_e32 v0, v1, v3
	s_waitcnt lgkmcnt(0)
	v_add_f32_e32 v1, v2, v4
	ds_bpermute_b32 v2, v115, v0
	ds_bpermute_b32 v3, v115, v1
	v_mov_b32_e32 v4, 0x7f800000
	s_waitcnt lgkmcnt(1)
	v_add_f32_e32 v0, v0, v2
	s_waitcnt lgkmcnt(0)
	v_add_f32_e32 v1, v1, v3
	v_mul_f32_e32 v2, 0x3fb8aa3b, v0
	v_mul_f32_e32 v3, 0x3fb8aa3b, v1
	v_fma_f32 v5, v0, s0, -v2
	v_rndne_f32_e32 v6, v2
	v_fma_f32 v7, v1, s0, -v3
	v_rndne_f32_e32 v8, v3
	v_fmac_f32_e32 v5, 0x32a5705f, v0
	v_sub_f32_e32 v2, v2, v6
	v_fmac_f32_e32 v7, 0x32a5705f, v1
	v_sub_f32_e32 v3, v3, v8
	v_add_f32_e32 v2, v2, v5
	v_cvt_i32_f32_e32 v6, v6
	v_add_f32_e32 v3, v3, v7
	v_exp_f32_e32 v2, v2
	v_cvt_i32_f32_e32 v8, v8
	v_exp_f32_e32 v3, v3
	v_cmp_ngt_f32_e32 vcc, s1, v0
	v_ldexp_f32 v2, v2, v6
	v_ldexp_f32 v3, v3, v8
	v_cndmask_b32_e32 v2, 0, v2, vcc
	v_cmp_ngt_f32_e32 vcc, s1, v1
	s_nop 1
	v_cndmask_b32_e32 v3, 0, v3, vcc
	v_cmp_nlt_f32_e32 vcc, s2, v0
	s_nop 1
	v_cndmask_b32_e32 v81, v4, v2, vcc
	v_cmp_nlt_f32_e32 vcc, s2, v1
	s_nop 1
	v_cndmask_b32_e32 v85, v4, v3, vcc
	s_cbranch_scc1 .LBB0_380
	v_bfe_u32 v123, v176, 5, 1
	v_lshlrev_b32_e32 v84, 2, v123
	v_or_b32_e32 v1, 1, v84
	v_or_b32_e32 v130, 2, v123
	v_or_b32_e32 v131, 4, v123
	v_or_b32_e32 v132, 6, v123
	v_or_b32_e32 v133, 8, v123
	v_or_b32_e32 v134, 10, v123
	v_or_b32_e32 v135, 12, v123
	v_or_b32_e32 v136, 14, v123
	v_or_b32_e32 v3, 3, v84
	v_or_b32_e32 v5, 2, v84
	v_or_b32_e32 v7, 9, v84
	v_or_b32_e32 v9, 8, v84
	v_or_b32_e32 v11, 11, v84
	v_or_b32_e32 v13, 10, v84
	v_or_b32_e32 v14, 17, v84
	v_or_b32_e32 v15, 16, v84
	v_or_b32_e32 v16, 19, v84
	v_or_b32_e32 v17, 18, v84
	v_or_b32_e32 v18, 25, v84
	v_or_b32_e32 v19, 24, v84
	v_or_b32_e32 v20, 27, v84
	v_or_b32_e32 v21, 26, v84
	v_lshlrev_b32_e32 v0, 2, v130
	v_lshlrev_b32_e32 v2, 2, v131
	v_lshlrev_b32_e32 v4, 2, v132
	v_lshlrev_b32_e32 v6, 2, v133
	v_lshlrev_b32_e32 v8, 2, v134
	v_lshlrev_b32_e32 v10, 2, v135
	v_lshlrev_b32_e32 v12, 2, v136
	v_cvt_f32_ubyte0_e32 v101, v1
	v_sub_u32_e32 v1, v114, v84
	v_lshlrev_b32_e32 v80, 3, v123
	v_mov_b32_e32 v83, 0
	s_mov_b32 s19, 0
	v_cmp_eq_u32_e64 s[0:1], 0, v123
	v_cvt_f32_ubyte0_e32 v87, v20
	v_cvt_f32_ubyte0_e32 v86, v21
	v_cvt_f32_ubyte0_e32 v89, v18
	v_cvt_f32_ubyte0_e32 v88, v19
	v_cvt_f32_ubyte0_e32 v91, v16
	v_cvt_f32_ubyte0_e32 v90, v17
	v_cvt_f32_ubyte0_e32 v93, v14
	v_cvt_f32_ubyte0_e32 v92, v15
	v_cvt_f32_ubyte0_e32 v95, v11
	v_cvt_f32_ubyte0_e32 v94, v13
	v_cvt_f32_ubyte0_e32 v97, v7
	v_cvt_f32_ubyte0_e32 v96, v9
	v_cvt_f32_ubyte0_e32 v99, v3
	v_cvt_f32_ubyte0_e32 v98, v5
	v_cvt_f32_ubyte0_e32 v100, v84
	v_or_b32_e32 v137, 0xffffff80, v114
	v_add_u32_e32 v138, 0x80, v1
	v_sub_u32_e32 v139, 0xffffff80, v114
	v_lshlrev_b32_e32 v102, 2, v114
	s_mov_b64 s[20:21], 0x2800
	s_movk_i32 s33, 0x3400
	s_mov_b64 s[22:23], 0x1000
	s_mov_b64 s[24:25], 0x1c00
	s_movk_i32 s44, 0x1000
	s_movk_i32 s45, 0x81
	s_mov_b32 s46, 0x5040100
	s_mov_b32 s98, 0x7060302
	v_lshlrev_b32_e32 v104, 1, v0
	v_lshlrev_b32_e32 v106, 1, v2
	v_lshlrev_b32_e32 v108, 1, v4
	v_lshlrev_b32_e32 v110, 1, v6
	v_lshlrev_b32_e32 v112, 1, v8
	v_lshlrev_b32_e32 v116, 1, v10
	v_lshlrev_b32_e32 v118, 1, v12
	v_mov_b32_e32 v140, 0xff800000
	s_branch .LBB0_315

; __device__ __forceinline__ int crow(int r, int hi) { return (r & 3) + 8 * (r >> 2) + 4 * hi; }
; __device__ __forceinline__ unsigned cvtpk(float lo, float hi) { return pg8::cvt_pk_bf16(lo, hi); }
; __device__ __forceinline__ float ex2(float v) { return __builtin_amdgcn_exp2f(v); }
; #define MFMA32(a, b, c) __builtin_amdgcn_mfma_f32_32x32x16_bf16((a), (b), (c), 0, 0, 0)
; __device__ __forceinline__ void unit(LAS unsigned char* lds, bf16_t* P1, int b, int h, int chunk) {
;     ...
;                           for (int j = 0; j < 8; ++j) { const int kvl = 16 * s + 8 * (j >> 2) + 4 * hi + (j & 3); const int tok = ((ib + kvl) << sh) + cls;
;                               vfr[2 * d + s][j] = (short)vbase0[(size_t)tok * LDP + d * 32]; } }
;                 __builtin_amdgcn_sched_barrier(0);
;                 f32x16 S = cb;
; #pragma unroll
;                 for (int ks = 0; ks < 4; ++ks) S = MFMA32(kfr[ks], qf[ks], S);
;                 if (kb == 0) {
; #pragma unroll
;                     for (int r = 0; r < 16; ++r) { const int ik = ib + crow(r, hi); if (iq - ik > 128) S[r] = -INFINITY; } }
;                 if (kb == 4) {
; #pragma unroll
;                     for (int r = 0; r < 16; ++r) { const int ik = ib + crow(r, hi); if (ik > iq) S[r] = -INFINITY; } }
;                 const float tb = sd * (float)(ib - iq);
;                 float mx = S[0];
; #pragma unroll
;                 for (int r = 1; r < 16; ++r) mx = fmaxf(mx, S[r]);
;                 float mt = mx + tb; mt = fmaxf(mt, __shfl_xor(mt, 32));
;                 const float mn = fmaxf(m, mt); const float alpha = ex2(m - mn); m = mn; const float c = tb - mn;
;                 float ps = 0.f;
; #pragma unroll
;                 for (int r = 0; r < 16; ++r) { S[r] = ex2(S[r] + c); ps += S[r]; }
;                 l = l * alpha + ps; O[0] = O[0] * alpha; O[1] = O[1] * alpha;
;                 u32x4 pk[2];
; #pragma unroll
;                 for (int s = 0; s < 2; ++s) pk[s] = (u32x4){cvtpk(S[8 * s + 0], S[8 * s + 1]), cvtpk(S[8 * s + 2], S[8 * s + 3]), cvtpk(S[8 * s + 4], S[8 * s + 5]), cvtpk(S[8 * s + 6], S[8 * s + 7])};
; #pragma unroll
;                 for (int d = 0; d < 2; ++d)
; #pragma unroll
;                     for (int s = 0; s < 2; ++s) O[d] = MFMA32(vfr[2 * d + s], __builtin_bit_cast(bf16x8, pk[s]), O[d]);
.LBB0_321:
	s_nop 7
	v_max_f32_e32 v174, v49, v49
	v_max_f32_e32 v175, v48, v48
	v_max_f32_e32 v174, v175, v174
	v_max3_f32 v174, v174, v50, v51
	v_max3_f32 v174, v174, v52, v53
	v_add_u32_e32 v173, s4, v139
	v_max3_f32 v174, v174, v54, v55
	v_cvt_f32_i32_e32 v173, v173
	v_max3_f32 v174, v174, v56, v57
	v_max3_f32 v174, v174, v58, v59
	v_max3_f32 v174, v174, v60, v61
	v_max3_f32 v174, v174, v62, v63
	v_fmac_f32_e32 v174, v122, v173
	ds_bpermute_b32 v175, v115, v174
	s_waitcnt lgkmcnt(0)
	v_max3_f32 v174, v117, v174, v175
	v_fma_f32 v173, v122, v173, -v174
	v_add_f32_e32 v48, v48, v173
	v_exp_f32_e32 v48, v48
	v_add_f32_e32 v49, v49, v173
	v_add_f32_e32 v50, v50, v173
	v_exp_f32_e32 v49, v49
	v_exp_f32_e32 v50, v50
	v_add_f32_e32 v51, v51, v173
	v_exp_f32_e32 v51, v51
	v_add_f32_e32 v52, v52, v173
	v_add_f32_e32 v175, 0, v48
	v_exp_f32_e32 v52, v52
	v_add_f32_e32 v53, v53, v173
	v_add_f32_e32 v175, v49, v175
	v_exp_f32_e32 v53, v53
	v_add_f32_e32 v54, v54, v173
	v_add_f32_e32 v175, v50, v175
	v_exp_f32_e32 v54, v54
	v_add_f32_e32 v55, v55, v173
	v_add_f32_e32 v175, v51, v175
	v_exp_f32_e32 v55, v55
	v_add_f32_e32 v56, v56, v173
	v_add_f32_e32 v175, v52, v175
	v_exp_f32_e32 v56, v56
	v_add_f32_e32 v57, v57, v173
	v_add_f32_e32 v175, v53, v175
	v_exp_f32_e32 v57, v57
	v_add_f32_e32 v58, v58, v173
	v_add_f32_e32 v175, v54, v175
	v_exp_f32_e32 v58, v58
	v_add_f32_e32 v59, v59, v173
	v_add_f32_e32 v175, v55, v175
	v_exp_f32_e32 v59, v59
	v_add_f32_e32 v60, v60, v173
	v_add_f32_e32 v175, v56, v175
	v_exp_f32_e32 v177, v60
	v_add_f32_e32 v60, v57, v175
	v_add_f32_e32 v60, v58, v60
	v_add_f32_e32 v60, v59, v60
	v_sub_f32_e32 v117, v117, v174
	v_add_f32_e32 v175, v177, v60
	v_add_f32_e32 v60, v61, v173
	v_exp_f32_e32 v61, v60
	v_exp_f32_e32 v60, v117
	v_cvt_pk_bf16_f32 v48, v48, v49
	v_cvt_pk_bf16_f32 v49, v50, v51
	v_cvt_pk_bf16_f32 v50, v52, v53
	v_cvt_pk_bf16_f32 v51, v54, v55
	s_waitcnt vmcnt(8)
	v_perm_b32 v55, v168, v167, s46
	v_perm_b32 v54, v166, v165, s46
	v_perm_b32 v53, v159, v156, s46
	v_perm_b32 v52, v154, v153, s46
	v_mul_f32_e32 v46, v60, v46
	v_mul_f32_e32 v47, v60, v47
	v_mul_f32_e32 v44, v60, v44
	v_mul_f32_e32 v45, v60, v45
	v_mul_f32_e32 v42, v60, v42
	v_mul_f32_e32 v43, v60, v43
	v_mul_f32_e32 v40, v60, v40
	v_mul_f32_e32 v41, v60, v41
	v_mul_f32_e32 v38, v60, v38
	v_mul_f32_e32 v39, v60, v39
	v_mul_f32_e32 v36, v60, v36
	v_mul_f32_e32 v37, v60, v37
	v_mul_f32_e32 v34, v60, v34
	v_mul_f32_e32 v35, v60, v35
	v_mul_f32_e32 v32, v60, v32
	v_mul_f32_e32 v33, v60, v33
	v_add_f32_e32 v62, v62, v173
	v_add_f32_e32 v63, v63, v173
	v_mfma_f32_32x32x16_bf16 v[32:47], v[52:55], v[48:51], v[32:47]
	v_exp_f32_e32 v62, v62
	v_exp_f32_e32 v63, v63
	s_waitcnt vmcnt(0)
	v_perm_b32 v55, v172, v171, s46
	v_perm_b32 v54, v170, v169, s46
	v_perm_b32 v53, v164, v163, s46
	v_perm_b32 v52, v162, v161, s46
	v_cvt_pk_bf16_f32 v56, v56, v57
	v_cvt_pk_bf16_f32 v57, v58, v59
	v_cvt_pk_bf16_f32 v58, v177, v61
	v_cvt_pk_bf16_f32 v59, v62, v63
	v_mul_f32_e32 v30, v60, v30
	v_mul_f32_e32 v31, v60, v31
	v_mul_f32_e32 v28, v60, v28
	v_mul_f32_e32 v29, v60, v29
	v_mfma_f32_32x32x16_bf16 v[32:47], v[52:55], v[56:59], v[32:47]
	v_perm_b32 v55, v168, v167, s98
	v_perm_b32 v54, v166, v165, s98
	v_perm_b32 v53, v159, v156, s98
	v_perm_b32 v52, v154, v153, s98
	v_mul_f32_e64 v26, v26, v60
	v_mul_f32_e64 v27, v27, v60
	v_mul_f32_e32 v24, v60, v24
	v_mul_f32_e32 v25, v60, v25
	v_mul_f32_e32 v22, v60, v22
	v_mul_f32_e32 v23, v60, v23
	v_mul_f32_e32 v20, v60, v20
	v_mul_f32_e32 v21, v60, v21
	v_mul_f32_e32 v18, v60, v18
	v_mul_f32_e32 v19, v60, v19
	v_mul_f32_e32 v16, v60, v16
	v_mul_f32_e32 v17, v60, v17
	v_mov_b32_e32 v117, v174
	s_nop 0
	v_mfma_f32_32x32x16_bf16 v[16:31], v[52:55], v[48:51], v[16:31]
	s_waitcnt vmcnt(2)
	v_perm_b32 v51, v172, v171, s98
	s_waitcnt vmcnt(0)
	v_perm_b32 v50, v170, v169, s98
	v_perm_b32 v49, v164, v163, s98
	v_perm_b32 v48, v162, v161, s98
	v_add_f32_e32 v52, v61, v175
	v_add_f32_e32 v52, v62, v52
	v_add_f32_e32 v52, v63, v52
	v_mfma_f32_32x32x16_bf16 v[16:31], v[48:51], v[56:59], v[16:31]
	v_fmac_f32_e32 v52, v113, v60
	v_mov_b32_e32 v113, v52

; #define MFMA32(a, b, c) __builtin_amdgcn_mfma_f32_32x32x16_bf16((a), (b), (c), 0, 0, 0)
; __device__ __forceinline__ void unit(LAS unsigned char* lds, bf16_t* P1, int b, int h, int chunk) {
;     ...
;             for (int kb = 0; kb < 5; ++kb) {
;                 const int ib = i0 - 128 + 32 * kb; if (ib < 0) continue;
;                 const int tk = ((ib + r32) << sh) + cls;
;                 const bf16_t* kp = P1 + (rowbase + tk) * LDP + C_KB + g * 512 + h * 64 + hi * 8;
;                 bf16x8 kfr[4];
; #pragma unroll
;                 for (int ks = 0; ks < 4; ++ks) kfr[ks] = *(const bf16x8*)(kp + ks * 16);
;                 bf16x8 vfr[4];
;                 { const bf16_t* vbase0 = P1 + rowbase * LDP + C_VB + g * 512 + h * 64 + r32;
; #pragma unroll
;                   for (int d = 0; d < 2; ++d)
; #pragma unroll
;                       for (int s = 0; s < 2; ++s)
; #pragma unroll
;                           for (int j = 0; j < 8; ++j) { const int kvl = 16 * s + 8 * (j >> 2) + 4 * hi + (j & 3); const int tok = ((ib + kvl) << sh) + cls;
;                               vfr[2 * d + s][j] = (short)vbase0[(size_t)tok * LDP + d * 32]; } }
;                 __builtin_amdgcn_sched_barrier(0);
;                 f32x16 S = cb;
; #pragma unroll
;                 for (int ks = 0; ks < 4; ++ks) S = MFMA32(kfr[ks], qf[ks], S);
.LBB0_323:
	s_add_i32 s5, s3, s4
	s_addk_i32 s5, 0xff80
	s_cmp_lt_i32 s5, 0
	s_cbranch_scc1 .LBB0_322
	v_add_u32_e32 v48, s4, v107
	v_lshlrev_b32_e32 v48, s50, v48
	v_add_u32_e32 v48, s2, v48
	v_ashrrev_i32_e32 v49, 31, v48
	v_lshl_add_u64 v[48:49], s[28:29], 0, v[48:49]
	v_mov_b64_e32 v[50:51], s[78:79]
	v_mad_u64_u32 v[50:51], s[42:43], v48, s33, v[50:51]
	v_mad_i32_i24 v51, v49, s33, v51
	v_lshl_add_u64 v[48:49], v[50:51], 0, s[18:19]
	s_mov_b32 s35, s19
	v_lshl_add_u64 v[48:49], v[48:49], 0, s[34:35]
	v_lshl_add_u64 v[48:49], v[48:49], 0, v[82:83]
	v_add_u32_e32 v119, s4, v109
	v_lshl_add_u64 v[50:51], v[48:49], 0, s[24:25]
	v_add_co_u32_e32 v48, vcc, s44, v48
	v_add_u32_e32 v173, 0xffffff90, v119
	s_nop 0
	v_addc_co_u32_e32 v49, vcc, 0, v49, vcc
	global_load_dwordx4 v[190:193], v[50:51], off offset:32
	global_load_dwordx4 v[194:197], v[50:51], off offset:64
	global_load_dwordx4 v[202:205], v[48:49], off offset:3072
	global_load_dwordx4 v[206:209], v[50:51], off offset:96
	v_lshlrev_b32_e32 v48, s50, v173
	v_add_u32_e32 v127, s2, v48
	v_add_u32_e32 v183, 0xffffff91, v119
	v_mad_i64_i32 v[170:171], s[42:43], v127, s33, v[124:125]
	v_lshlrev_b32_e32 v127, s50, v183
	v_add_u32_e32 v127, s2, v127
	v_add_u32_e32 v184, 0xffffff92, v119
	v_mad_i64_i32 v[198:199], s[42:43], v127, s33, v[124:125]
	v_lshlrev_b32_e32 v127, s50, v184
	v_add_u32_e32 v127, s2, v127
	v_add_u32_e32 v185, 0xffffff93, v119
	v_mad_i64_i32 v[146:147], s[42:43], v127, s33, v[124:125]
	v_lshlrev_b32_e32 v127, s50, v185
	v_add_u32_e32 v127, s2, v127
	v_add_u32_e32 v186, 0xffffff98, v119
	v_mad_i64_i32 v[210:211], s[42:43], v127, s33, v[124:125]
	v_lshlrev_b32_e32 v127, s50, v186
	v_add_u32_e32 v127, s2, v127
	v_add_u32_e32 v187, 0xffffff99, v119
	v_add_u32_e32 v174, 0xffffff80, v119
	v_mad_i64_i32 v[212:213], s[42:43], v127, s33, v[124:125]
	v_lshlrev_b32_e32 v127, s50, v187
	v_lshlrev_b32_e32 v48, s50, v174
	v_add_u32_e32 v175, 0xffffff81, v119
	v_add_u32_e32 v177, 0xffffff82, v119
	v_add_u32_e32 v178, 0xffffff83, v119
	v_add_u32_e32 v179, 0xffffff88, v119
	v_add_u32_e32 v180, 0xffffff89, v119
	v_add_u32_e32 v181, 0xffffff8a, v119
	v_add_u32_e32 v182, 0xffffff8b, v119
	v_add_u32_e32 v127, s2, v127
	v_add_u32_e32 v188, 0xffffff9a, v119
	v_add_u32_e32 v189, 0xffffff9b, v119
	v_add_u32_e32 v48, s2, v48
	v_lshlrev_b32_e32 v50, s50, v175
	v_lshlrev_b32_e32 v52, s50, v177
	v_lshlrev_b32_e32 v54, s50, v178
	v_lshlrev_b32_e32 v56, s50, v179
	v_lshlrev_b32_e32 v58, s50, v180
	v_lshlrev_b32_e32 v60, s50, v181
	v_lshlrev_b32_e32 v62, s50, v182
	v_mad_i64_i32 v[214:215], s[42:43], v127, s33, v[124:125]
	v_lshlrev_b32_e32 v127, s50, v188
	v_lshlrev_b32_e32 v119, s50, v189
	v_mad_i64_i32 v[48:49], s[42:43], v48, s33, v[124:125]
	v_add_u32_e32 v50, s2, v50
	v_add_u32_e32 v52, s2, v52
	v_add_u32_e32 v54, s2, v54
	v_add_u32_e32 v56, s2, v56
	v_add_u32_e32 v58, s2, v58
	v_add_u32_e32 v60, s2, v60
	v_add_u32_e32 v62, s2, v62
	v_add_u32_e32 v127, s2, v127
	v_add_u32_e32 v119, s2, v119
	v_mad_i64_i32 v[50:51], s[42:43], v50, s33, v[124:125]
	v_mad_i64_i32 v[52:53], s[42:43], v52, s33, v[124:125]
	v_mad_i64_i32 v[54:55], s[42:43], v54, s33, v[124:125]
	v_mad_i64_i32 v[56:57], s[42:43], v56, s33, v[124:125]
	v_mad_i64_i32 v[58:59], s[42:43], v58, s33, v[124:125]
	v_mad_i64_i32 v[60:61], s[42:43], v60, s33, v[124:125]
	v_mad_i64_i32 v[62:63], s[42:43], v62, s33, v[124:125]
	v_mad_i64_i32 v[216:217], s[42:43], v127, s33, v[124:125]
	v_mad_i64_i32 v[218:219], s[42:43], v119, s33, v[124:125]
	global_load_dword v153, v[48:49], off
	global_load_dword v154, v[50:51], off
	global_load_dword v156, v[52:53], off
	global_load_dword v159, v[54:55], off
	global_load_dword v165, v[56:57], off
	global_load_dword v166, v[58:59], off
	global_load_dword v167, v[60:61], off
	global_load_dword v168, v[62:63], off
	global_load_dword v161, v[170:171], off
	global_load_dword v162, v[198:199], off
	global_load_dword v163, v[146:147], off
	global_load_dword v164, v[210:211], off
	s_nop 0
	s_nop 0
	global_load_dword v169, v[212:213], off
	s_nop 0
	global_load_dword v170, v[214:215], off
	global_load_dword v171, v[216:217], off
	global_load_dword v172, v[218:219], off
	s_waitcnt vmcnt(17)
	v_mfma_f32_32x32x16_bf16 v[48:63], v[202:205], v[64:67], v[0:15]
	s_cmp_lg_u32 s4, 0
	v_mfma_f32_32x32x16_bf16 v[48:63], v[190:193], v[68:71], v[48:63]
	v_mfma_f32_32x32x16_bf16 v[48:63], v[194:197], v[72:75], v[48:63]
	s_waitcnt vmcnt(16)
	v_mfma_f32_32x32x16_bf16 v[48:63], v[206:209], v[76:79], v[48:63]
	s_cbranch_scc0 .LBB0_326
	s_cmpk_lg_i32 s4, 0x80
	s_cbranch_scc1 .LBB0_321
	s_branch .LBB0_327
